# scan recurrence waves run at s_setprio 1 inside the chunk block (on top of attention fast path v2)
# speedup vs baseline: 1.0060x; 1.0030x over previous
.LBB0_545:
	s_setprio 1
	s_mul_i32 s4, s93, 0x6000
	s_lshl_b32 s5, s93, 14
	v_add_u32_e32 v2, s4, v194
	v_add_u32_e32 v3, s4, v195
	v_add_u32_e32 v0, s5, v196
	v_xor_b32_e32 v53, 4, v3
	ds_read_b128 v[24:27], v2 offset:16384
	ds_read_b32 v44, v3 offset:12288
	ds_read_b32 v45, v53 offset:12288
	ds_read_b128 v[36:39], v2 offset:8192
	ds_read_b128 v[28:31], v2 offset:4096
	ds_read_b128 v[32:35], v2 offset:20480
	ds_read_b128 v[40:43], v2 offset:0
	ds_read_b128 v[144:147], v2 offset:16640
	ds_read_b32 v164, v3 offset:12544
	ds_read_b32 v165, v53 offset:12544
	ds_read_b128 v[156:159], v2 offset:8448
	ds_read_b128 v[148:151], v2 offset:4352
	ds_read_b128 v[152:155], v2 offset:20736
	s_waitcnt lgkmcnt(6)
	v_pk_mul_f32 v[46:47], v[16:17], v[24:25] op_sel_hi:[1,0]
	v_pk_fma_f32 v[46:47], v[18:19], v[24:25], v[46:47] op_sel:[0,1,0] op_sel_hi:[1,1,1]
	v_pk_fma_f32 v[46:47], v[20:21], v[26:27], v[46:47] op_sel_hi:[1,0,1]
	v_pk_fma_f32 v[46:47], v[22:23], v[26:27], v[46:47] op_sel:[0,1,0] op_sel_hi:[1,1,1]
	ds_read_b128 v[160:163], v2 offset:256
	v_pk_mul_f32 v[168:169], v[44:45], v[36:37] op_sel_hi:[1,0]
	v_add_f32_dpp v48, v47, v46 quad_perm:[1,0,3,2] row_mask:0xf bank_mask:0xf bound_ctrl:1
	v_pk_mul_f32 v[170:171], v[44:45], v[36:37] op_sel:[0,1] op_sel_hi:[1,1]
	s_nop 0
	v_add_f32_dpp v48, v48, v48 quad_perm:[2,3,0,1] row_mask:0xf bank_mask:0xf bound_ctrl:1
	v_pk_mul_f32 v[172:173], v[44:45], v[38:39] op_sel_hi:[1,0]
	v_pk_mul_f32 v[174:175], v[44:45], v[38:39] op_sel:[0,1] op_sel_hi:[1,1]
	v_add_f32_dpp v48, v48, v48 row_ror:4 row_mask:0xf bank_mask:0xf bound_ctrl:1
	v_pk_fma_f32 v[168:169], v[16:17], v[28:29], v[168:169] op_sel_hi:[1,0,1]
	v_pk_fma_f32 v[170:171], v[18:19], v[28:29], v[170:171] op_sel:[0,1,0] op_sel_hi:[1,1,1]
	v_add_f32_dpp v48, v48, v48 row_ror:8 row_mask:0xf bank_mask:0xf bound_ctrl:1
	v_pk_fma_f32 v[172:173], v[20:21], v[30:31], v[172:173] op_sel_hi:[1,0,1]
	v_pk_fma_f32 v[174:175], v[22:23], v[30:31], v[174:175] op_sel:[0,1,0] op_sel_hi:[1,1,1]
	v_mov_b32_dpp v49, v48 quad_perm:[1,0,3,2] row_mask:0xf bank_mask:0xf bound_ctrl:1
	v_pk_fma_f32 v[16:17], v[48:49], v[32:33], v[168:169] op_sel_hi:[1,0,1] neg_lo:[0,1,0] neg_hi:[0,1,0]
	v_pk_fma_f32 v[18:19], v[48:49], v[32:33], v[170:171] op_sel:[0,1,0] op_sel_hi:[1,1,1] neg_lo:[0,1,0] neg_hi:[0,1,0]
	v_pk_fma_f32 v[20:21], v[48:49], v[34:35], v[172:173] op_sel_hi:[1,0,1] neg_lo:[0,1,0] neg_hi:[0,1,0]
	v_pk_fma_f32 v[22:23], v[48:49], v[34:35], v[174:175] op_sel:[0,1,0] op_sel_hi:[1,1,1] neg_lo:[0,1,0] neg_hi:[0,1,0]
	ds_read_b128 v[24:27], v2 offset:16896
	ds_read_b32 v44, v3 offset:12800
	ds_read_b32 v45, v53 offset:12800
	ds_read_b128 v[36:39], v2 offset:8704
	ds_read_b128 v[28:31], v2 offset:4608
	ds_read_b128 v[32:35], v2 offset:20992
	s_waitcnt lgkmcnt(6)
	v_pk_mul_f32 v[46:47], v[16:17], v[144:145] op_sel_hi:[1,0]
	v_pk_mul_f32 v[50:51], v[16:17], v[40:41] op_sel_hi:[1,0]
	v_pk_fma_f32 v[46:47], v[18:19], v[144:145], v[46:47] op_sel:[0,1,0] op_sel_hi:[1,1,1]
	v_pk_fma_f32 v[50:51], v[18:19], v[40:41], v[50:51] op_sel:[0,1,0] op_sel_hi:[1,1,1]
	v_pk_fma_f32 v[46:47], v[20:21], v[146:147], v[46:47] op_sel_hi:[1,0,1]
	v_pk_fma_f32 v[50:51], v[20:21], v[42:43], v[50:51] op_sel_hi:[1,0,1]
	v_pk_fma_f32 v[46:47], v[22:23], v[146:147], v[46:47] op_sel:[0,1,0] op_sel_hi:[1,1,1]
	v_pk_fma_f32 v[50:51], v[22:23], v[42:43], v[50:51] op_sel:[0,1,0] op_sel_hi:[1,1,1]
	ds_read_b128 v[40:43], v2 offset:512
	v_pk_mul_f32 v[168:169], v[164:165], v[156:157] op_sel_hi:[1,0]
	v_add_f32_dpp v48, v47, v46 quad_perm:[1,0,3,2] row_mask:0xf bank_mask:0xf bound_ctrl:1
	v_add_f32_dpp v52, v51, v50 quad_perm:[1,0,3,2] row_mask:0xf bank_mask:0xf bound_ctrl:1
	v_pk_mul_f32 v[170:171], v[164:165], v[156:157] op_sel:[0,1] op_sel_hi:[1,1]
	v_add_f32_dpp v48, v48, v48 quad_perm:[2,3,0,1] row_mask:0xf bank_mask:0xf bound_ctrl:1
	ds_write_b32 v0, v52 offset:49152
	v_pk_mul_f32 v[172:173], v[164:165], v[158:159] op_sel_hi:[1,0]
	v_pk_mul_f32 v[174:175], v[164:165], v[158:159] op_sel:[0,1] op_sel_hi:[1,1]
	v_add_f32_dpp v48, v48, v48 row_ror:4 row_mask:0xf bank_mask:0xf bound_ctrl:1
	v_pk_fma_f32 v[168:169], v[16:17], v[148:149], v[168:169] op_sel_hi:[1,0,1]
	v_pk_fma_f32 v[170:171], v[18:19], v[148:149], v[170:171] op_sel:[0,1,0] op_sel_hi:[1,1,1]
	v_add_f32_dpp v48, v48, v48 row_ror:8 row_mask:0xf bank_mask:0xf bound_ctrl:1
	v_pk_fma_f32 v[172:173], v[20:21], v[150:151], v[172:173] op_sel_hi:[1,0,1]
	v_pk_fma_f32 v[174:175], v[22:23], v[150:151], v[174:175] op_sel:[0,1,0] op_sel_hi:[1,1,1]
	v_mov_b32_dpp v49, v48 quad_perm:[1,0,3,2] row_mask:0xf bank_mask:0xf bound_ctrl:1
	v_pk_fma_f32 v[16:17], v[48:49], v[152:153], v[168:169] op_sel_hi:[1,0,1] neg_lo:[0,1,0] neg_hi:[0,1,0]
	v_pk_fma_f32 v[18:19], v[48:49], v[152:153], v[170:171] op_sel:[0,1,0] op_sel_hi:[1,1,1] neg_lo:[0,1,0] neg_hi:[0,1,0]
	v_pk_fma_f32 v[20:21], v[48:49], v[154:155], v[172:173] op_sel_hi:[1,0,1] neg_lo:[0,1,0] neg_hi:[0,1,0]
	v_pk_fma_f32 v[22:23], v[48:49], v[154:155], v[174:175] op_sel:[0,1,0] op_sel_hi:[1,1,1] neg_lo:[0,1,0] neg_hi:[0,1,0]
	ds_read_b128 v[144:147], v2 offset:17152
	ds_read_b32 v164, v3 offset:13056
	ds_read_b32 v165, v53 offset:13056
	ds_read_b128 v[156:159], v2 offset:8960
	ds_read_b128 v[148:151], v2 offset:4864
	ds_read_b128 v[152:155], v2 offset:21248
	s_waitcnt lgkmcnt(7)
	v_pk_mul_f32 v[46:47], v[16:17], v[24:25] op_sel_hi:[1,0]
	v_pk_mul_f32 v[50:51], v[16:17], v[160:161] op_sel_hi:[1,0]
	v_pk_fma_f32 v[46:47], v[18:19], v[24:25], v[46:47] op_sel:[0,1,0] op_sel_hi:[1,1,1]
	v_pk_fma_f32 v[50:51], v[18:19], v[160:161], v[50:51] op_sel:[0,1,0] op_sel_hi:[1,1,1]
	v_pk_fma_f32 v[46:47], v[20:21], v[26:27], v[46:47] op_sel_hi:[1,0,1]
	v_pk_fma_f32 v[50:51], v[20:21], v[162:163], v[50:51] op_sel_hi:[1,0,1]
	v_pk_fma_f32 v[46:47], v[22:23], v[26:27], v[46:47] op_sel:[0,1,0] op_sel_hi:[1,1,1]
	v_pk_fma_f32 v[50:51], v[22:23], v[162:163], v[50:51] op_sel:[0,1,0] op_sel_hi:[1,1,1]
	ds_read_b128 v[160:163], v2 offset:768
	v_pk_mul_f32 v[168:169], v[44:45], v[36:37] op_sel_hi:[1,0]
	v_add_f32_dpp v48, v47, v46 quad_perm:[1,0,3,2] row_mask:0xf bank_mask:0xf bound_ctrl:1
	v_add_f32_dpp v52, v51, v50 quad_perm:[1,0,3,2] row_mask:0xf bank_mask:0xf bound_ctrl:1
	v_pk_mul_f32 v[170:171], v[44:45], v[36:37] op_sel:[0,1] op_sel_hi:[1,1]
	v_add_f32_dpp v48, v48, v48 quad_perm:[2,3,0,1] row_mask:0xf bank_mask:0xf bound_ctrl:1
	ds_write_b32 v0, v52 offset:50176
	v_pk_mul_f32 v[172:173], v[44:45], v[38:39] op_sel_hi:[1,0]
	v_pk_mul_f32 v[174:175], v[44:45], v[38:39] op_sel:[0,1] op_sel_hi:[1,1]
	v_add_f32_dpp v48, v48, v48 row_ror:4 row_mask:0xf bank_mask:0xf bound_ctrl:1
	v_pk_fma_f32 v[168:169], v[16:17], v[28:29], v[168:169] op_sel_hi:[1,0,1]
	v_pk_fma_f32 v[170:171], v[18:19], v[28:29], v[170:171] op_sel:[0,1,0] op_sel_hi:[1,1,1]
	v_add_f32_dpp v48, v48, v48 row_ror:8 row_mask:0xf bank_mask:0xf bound_ctrl:1
	v_pk_fma_f32 v[172:173], v[20:21], v[30:31], v[172:173] op_sel_hi:[1,0,1]
	v_pk_fma_f32 v[174:175], v[22:23], v[30:31], v[174:175] op_sel:[0,1,0] op_sel_hi:[1,1,1]
	v_mov_b32_dpp v49, v48 quad_perm:[1,0,3,2] row_mask:0xf bank_mask:0xf bound_ctrl:1
	v_pk_fma_f32 v[16:17], v[48:49], v[32:33], v[168:169] op_sel_hi:[1,0,1] neg_lo:[0,1,0] neg_hi:[0,1,0]
	v_pk_fma_f32 v[18:19], v[48:49], v[32:33], v[170:171] op_sel:[0,1,0] op_sel_hi:[1,1,1] neg_lo:[0,1,0] neg_hi:[0,1,0]
	v_pk_fma_f32 v[20:21], v[48:49], v[34:35], v[172:173] op_sel_hi:[1,0,1] neg_lo:[0,1,0] neg_hi:[0,1,0]
	v_pk_fma_f32 v[22:23], v[48:49], v[34:35], v[174:175] op_sel:[0,1,0] op_sel_hi:[1,1,1] neg_lo:[0,1,0] neg_hi:[0,1,0]
	ds_read_b128 v[24:27], v2 offset:17408
	ds_read_b32 v44, v3 offset:13312
	ds_read_b32 v45, v53 offset:13312
	ds_read_b128 v[36:39], v2 offset:9216
	ds_read_b128 v[28:31], v2 offset:5120
	ds_read_b128 v[32:35], v2 offset:21504
	s_waitcnt lgkmcnt(7)
	v_pk_mul_f32 v[46:47], v[16:17], v[144:145] op_sel_hi:[1,0]
	v_pk_mul_f32 v[50:51], v[16:17], v[40:41] op_sel_hi:[1,0]
	v_pk_fma_f32 v[46:47], v[18:19], v[144:145], v[46:47] op_sel:[0,1,0] op_sel_hi:[1,1,1]
	v_pk_fma_f32 v[50:51], v[18:19], v[40:41], v[50:51] op_sel:[0,1,0] op_sel_hi:[1,1,1]
	v_pk_fma_f32 v[46:47], v[20:21], v[146:147], v[46:47] op_sel_hi:[1,0,1]
	v_pk_fma_f32 v[50:51], v[20:21], v[42:43], v[50:51] op_sel_hi:[1,0,1]
	v_pk_fma_f32 v[46:47], v[22:23], v[146:147], v[46:47] op_sel:[0,1,0] op_sel_hi:[1,1,1]
	v_pk_fma_f32 v[50:51], v[22:23], v[42:43], v[50:51] op_sel:[0,1,0] op_sel_hi:[1,1,1]
	ds_read_b128 v[40:43], v2 offset:1024
	v_pk_mul_f32 v[168:169], v[164:165], v[156:157] op_sel_hi:[1,0]
	v_add_f32_dpp v48, v47, v46 quad_perm:[1,0,3,2] row_mask:0xf bank_mask:0xf bound_ctrl:1
	v_add_f32_dpp v52, v51, v50 quad_perm:[1,0,3,2] row_mask:0xf bank_mask:0xf bound_ctrl:1
	v_pk_mul_f32 v[170:171], v[164:165], v[156:157] op_sel:[0,1] op_sel_hi:[1,1]
	v_add_f32_dpp v48, v48, v48 quad_perm:[2,3,0,1] row_mask:0xf bank_mask:0xf bound_ctrl:1
	ds_write_b32 v0, v52 offset:51200
	v_pk_mul_f32 v[172:173], v[164:165], v[158:159] op_sel_hi:[1,0]
	v_pk_mul_f32 v[174:175], v[164:165], v[158:159] op_sel:[0,1] op_sel_hi:[1,1]
	v_add_f32_dpp v48, v48, v48 row_ror:4 row_mask:0xf bank_mask:0xf bound_ctrl:1
	v_pk_fma_f32 v[168:169], v[16:17], v[148:149], v[168:169] op_sel_hi:[1,0,1]
	v_pk_fma_f32 v[170:171], v[18:19], v[148:149], v[170:171] op_sel:[0,1,0] op_sel_hi:[1,1,1]
	v_add_f32_dpp v48, v48, v48 row_ror:8 row_mask:0xf bank_mask:0xf bound_ctrl:1
	v_pk_fma_f32 v[172:173], v[20:21], v[150:151], v[172:173] op_sel_hi:[1,0,1]
	v_pk_fma_f32 v[174:175], v[22:23], v[150:151], v[174:175] op_sel:[0,1,0] op_sel_hi:[1,1,1]
	v_mov_b32_dpp v49, v48 quad_perm:[1,0,3,2] row_mask:0xf bank_mask:0xf bound_ctrl:1
	v_pk_fma_f32 v[16:17], v[48:49], v[152:153], v[168:169] op_sel_hi:[1,0,1] neg_lo:[0,1,0] neg_hi:[0,1,0]
	v_pk_fma_f32 v[18:19], v[48:49], v[152:153], v[170:171] op_sel:[0,1,0] op_sel_hi:[1,1,1] neg_lo:[0,1,0] neg_hi:[0,1,0]
	v_pk_fma_f32 v[20:21], v[48:49], v[154:155], v[172:173] op_sel_hi:[1,0,1] neg_lo:[0,1,0] neg_hi:[0,1,0]
	v_pk_fma_f32 v[22:23], v[48:49], v[154:155], v[174:175] op_sel:[0,1,0] op_sel_hi:[1,1,1] neg_lo:[0,1,0] neg_hi:[0,1,0]
	ds_read_b128 v[144:147], v2 offset:17664
	ds_read_b32 v164, v3 offset:13568
	ds_read_b32 v165, v53 offset:13568
	ds_read_b128 v[156:159], v2 offset:9472
	ds_read_b128 v[148:151], v2 offset:5376
	ds_read_b128 v[152:155], v2 offset:21760
	s_waitcnt lgkmcnt(7)
	v_pk_mul_f32 v[46:47], v[16:17], v[24:25] op_sel_hi:[1,0]
	v_pk_mul_f32 v[50:51], v[16:17], v[160:161] op_sel_hi:[1,0]
	v_pk_fma_f32 v[46:47], v[18:19], v[24:25], v[46:47] op_sel:[0,1,0] op_sel_hi:[1,1,1]
	v_pk_fma_f32 v[50:51], v[18:19], v[160:161], v[50:51] op_sel:[0,1,0] op_sel_hi:[1,1,1]
	v_pk_fma_f32 v[46:47], v[20:21], v[26:27], v[46:47] op_sel_hi:[1,0,1]
	v_pk_fma_f32 v[50:51], v[20:21], v[162:163], v[50:51] op_sel_hi:[1,0,1]
	v_pk_fma_f32 v[46:47], v[22:23], v[26:27], v[46:47] op_sel:[0,1,0] op_sel_hi:[1,1,1]
	v_pk_fma_f32 v[50:51], v[22:23], v[162:163], v[50:51] op_sel:[0,1,0] op_sel_hi:[1,1,1]
	ds_read_b128 v[160:163], v2 offset:1280
	v_pk_mul_f32 v[168:169], v[44:45], v[36:37] op_sel_hi:[1,0]
	v_add_f32_dpp v48, v47, v46 quad_perm:[1,0,3,2] row_mask:0xf bank_mask:0xf bound_ctrl:1
	v_add_f32_dpp v52, v51, v50 quad_perm:[1,0,3,2] row_mask:0xf bank_mask:0xf bound_ctrl:1
	v_pk_mul_f32 v[170:171], v[44:45], v[36:37] op_sel:[0,1] op_sel_hi:[1,1]
	v_add_f32_dpp v48, v48, v48 quad_perm:[2,3,0,1] row_mask:0xf bank_mask:0xf bound_ctrl:1
	ds_write_b32 v0, v52 offset:52224
	v_pk_mul_f32 v[172:173], v[44:45], v[38:39] op_sel_hi:[1,0]
	v_pk_mul_f32 v[174:175], v[44:45], v[38:39] op_sel:[0,1] op_sel_hi:[1,1]
	v_add_f32_dpp v48, v48, v48 row_ror:4 row_mask:0xf bank_mask:0xf bound_ctrl:1
	v_pk_fma_f32 v[168:169], v[16:17], v[28:29], v[168:169] op_sel_hi:[1,0,1]
	v_pk_fma_f32 v[170:171], v[18:19], v[28:29], v[170:171] op_sel:[0,1,0] op_sel_hi:[1,1,1]
	v_add_f32_dpp v48, v48, v48 row_ror:8 row_mask:0xf bank_mask:0xf bound_ctrl:1
	v_pk_fma_f32 v[172:173], v[20:21], v[30:31], v[172:173] op_sel_hi:[1,0,1]
	v_pk_fma_f32 v[174:175], v[22:23], v[30:31], v[174:175] op_sel:[0,1,0] op_sel_hi:[1,1,1]
	v_mov_b32_dpp v49, v48 quad_perm:[1,0,3,2] row_mask:0xf bank_mask:0xf bound_ctrl:1
	v_pk_fma_f32 v[16:17], v[48:49], v[32:33], v[168:169] op_sel_hi:[1,0,1] neg_lo:[0,1,0] neg_hi:[0,1,0]
	v_pk_fma_f32 v[18:19], v[48:49], v[32:33], v[170:171] op_sel:[0,1,0] op_sel_hi:[1,1,1] neg_lo:[0,1,0] neg_hi:[0,1,0]
	v_pk_fma_f32 v[20:21], v[48:49], v[34:35], v[172:173] op_sel_hi:[1,0,1] neg_lo:[0,1,0] neg_hi:[0,1,0]
	v_pk_fma_f32 v[22:23], v[48:49], v[34:35], v[174:175] op_sel:[0,1,0] op_sel_hi:[1,1,1] neg_lo:[0,1,0] neg_hi:[0,1,0]
	ds_read_b128 v[24:27], v2 offset:17920
	ds_read_b32 v44, v3 offset:13824
	ds_read_b32 v45, v53 offset:13824
	ds_read_b128 v[36:39], v2 offset:9728
	ds_read_b128 v[28:31], v2 offset:5632
	ds_read_b128 v[32:35], v2 offset:22016
	s_waitcnt lgkmcnt(7)
	v_pk_mul_f32 v[46:47], v[16:17], v[144:145] op_sel_hi:[1,0]
	v_pk_mul_f32 v[50:51], v[16:17], v[40:41] op_sel_hi:[1,0]
	v_pk_fma_f32 v[46:47], v[18:19], v[144:145], v[46:47] op_sel:[0,1,0] op_sel_hi:[1,1,1]
	v_pk_fma_f32 v[50:51], v[18:19], v[40:41], v[50:51] op_sel:[0,1,0] op_sel_hi:[1,1,1]
	v_pk_fma_f32 v[46:47], v[20:21], v[146:147], v[46:47] op_sel_hi:[1,0,1]
	v_pk_fma_f32 v[50:51], v[20:21], v[42:43], v[50:51] op_sel_hi:[1,0,1]
	v_pk_fma_f32 v[46:47], v[22:23], v[146:147], v[46:47] op_sel:[0,1,0] op_sel_hi:[1,1,1]
	v_pk_fma_f32 v[50:51], v[22:23], v[42:43], v[50:51] op_sel:[0,1,0] op_sel_hi:[1,1,1]
	ds_read_b128 v[40:43], v2 offset:1536
	v_pk_mul_f32 v[168:169], v[164:165], v[156:157] op_sel_hi:[1,0]
	v_add_f32_dpp v48, v47, v46 quad_perm:[1,0,3,2] row_mask:0xf bank_mask:0xf bound_ctrl:1
	v_add_f32_dpp v52, v51, v50 quad_perm:[1,0,3,2] row_mask:0xf bank_mask:0xf bound_ctrl:1
	v_pk_mul_f32 v[170:171], v[164:165], v[156:157] op_sel:[0,1] op_sel_hi:[1,1]
	v_add_f32_dpp v48, v48, v48 quad_perm:[2,3,0,1] row_mask:0xf bank_mask:0xf bound_ctrl:1
	ds_write_b32 v0, v52 offset:53248
	v_pk_mul_f32 v[172:173], v[164:165], v[158:159] op_sel_hi:[1,0]
	v_pk_mul_f32 v[174:175], v[164:165], v[158:159] op_sel:[0,1] op_sel_hi:[1,1]
	v_add_f32_dpp v48, v48, v48 row_ror:4 row_mask:0xf bank_mask:0xf bound_ctrl:1
	v_pk_fma_f32 v[168:169], v[16:17], v[148:149], v[168:169] op_sel_hi:[1,0,1]
	v_pk_fma_f32 v[170:171], v[18:19], v[148:149], v[170:171] op_sel:[0,1,0] op_sel_hi:[1,1,1]
	v_add_f32_dpp v48, v48, v48 row_ror:8 row_mask:0xf bank_mask:0xf bound_ctrl:1
	v_pk_fma_f32 v[172:173], v[20:21], v[150:151], v[172:173] op_sel_hi:[1,0,1]
	v_pk_fma_f32 v[174:175], v[22:23], v[150:151], v[174:175] op_sel:[0,1,0] op_sel_hi:[1,1,1]
	v_mov_b32_dpp v49, v48 quad_perm:[1,0,3,2] row_mask:0xf bank_mask:0xf bound_ctrl:1
	v_pk_fma_f32 v[16:17], v[48:49], v[152:153], v[168:169] op_sel_hi:[1,0,1] neg_lo:[0,1,0] neg_hi:[0,1,0]
	v_pk_fma_f32 v[18:19], v[48:49], v[152:153], v[170:171] op_sel:[0,1,0] op_sel_hi:[1,1,1] neg_lo:[0,1,0] neg_hi:[0,1,0]
	v_pk_fma_f32 v[20:21], v[48:49], v[154:155], v[172:173] op_sel_hi:[1,0,1] neg_lo:[0,1,0] neg_hi:[0,1,0]
	v_pk_fma_f32 v[22:23], v[48:49], v[154:155], v[174:175] op_sel:[0,1,0] op_sel_hi:[1,1,1] neg_lo:[0,1,0] neg_hi:[0,1,0]
	ds_read_b128 v[144:147], v2 offset:18176
	ds_read_b32 v164, v3 offset:14080
	ds_read_b32 v165, v53 offset:14080
	ds_read_b128 v[156:159], v2 offset:9984
	ds_read_b128 v[148:151], v2 offset:5888
	ds_read_b128 v[152:155], v2 offset:22272
	s_waitcnt lgkmcnt(7)
	v_pk_mul_f32 v[46:47], v[16:17], v[24:25] op_sel_hi:[1,0]
	v_pk_mul_f32 v[50:51], v[16:17], v[160:161] op_sel_hi:[1,0]
	v_pk_fma_f32 v[46:47], v[18:19], v[24:25], v[46:47] op_sel:[0,1,0] op_sel_hi:[1,1,1]
	v_pk_fma_f32 v[50:51], v[18:19], v[160:161], v[50:51] op_sel:[0,1,0] op_sel_hi:[1,1,1]
	v_pk_fma_f32 v[46:47], v[20:21], v[26:27], v[46:47] op_sel_hi:[1,0,1]
	v_pk_fma_f32 v[50:51], v[20:21], v[162:163], v[50:51] op_sel_hi:[1,0,1]
	v_pk_fma_f32 v[46:47], v[22:23], v[26:27], v[46:47] op_sel:[0,1,0] op_sel_hi:[1,1,1]
	v_pk_fma_f32 v[50:51], v[22:23], v[162:163], v[50:51] op_sel:[0,1,0] op_sel_hi:[1,1,1]
	ds_read_b128 v[160:163], v2 offset:1792
	v_pk_mul_f32 v[168:169], v[44:45], v[36:37] op_sel_hi:[1,0]
	v_add_f32_dpp v48, v47, v46 quad_perm:[1,0,3,2] row_mask:0xf bank_mask:0xf bound_ctrl:1
	v_add_f32_dpp v52, v51, v50 quad_perm:[1,0,3,2] row_mask:0xf bank_mask:0xf bound_ctrl:1
	v_pk_mul_f32 v[170:171], v[44:45], v[36:37] op_sel:[0,1] op_sel_hi:[1,1]
	v_add_f32_dpp v48, v48, v48 quad_perm:[2,3,0,1] row_mask:0xf bank_mask:0xf bound_ctrl:1
	ds_write_b32 v0, v52 offset:54272
	v_pk_mul_f32 v[172:173], v[44:45], v[38:39] op_sel_hi:[1,0]
	v_pk_mul_f32 v[174:175], v[44:45], v[38:39] op_sel:[0,1] op_sel_hi:[1,1]
	v_add_f32_dpp v48, v48, v48 row_ror:4 row_mask:0xf bank_mask:0xf bound_ctrl:1
	v_pk_fma_f32 v[168:169], v[16:17], v[28:29], v[168:169] op_sel_hi:[1,0,1]
	v_pk_fma_f32 v[170:171], v[18:19], v[28:29], v[170:171] op_sel:[0,1,0] op_sel_hi:[1,1,1]
	v_add_f32_dpp v48, v48, v48 row_ror:8 row_mask:0xf bank_mask:0xf bound_ctrl:1
	v_pk_fma_f32 v[172:173], v[20:21], v[30:31], v[172:173] op_sel_hi:[1,0,1]
	v_pk_fma_f32 v[174:175], v[22:23], v[30:31], v[174:175] op_sel:[0,1,0] op_sel_hi:[1,1,1]
	v_mov_b32_dpp v49, v48 quad_perm:[1,0,3,2] row_mask:0xf bank_mask:0xf bound_ctrl:1
	v_pk_fma_f32 v[16:17], v[48:49], v[32:33], v[168:169] op_sel_hi:[1,0,1] neg_lo:[0,1,0] neg_hi:[0,1,0]
	v_pk_fma_f32 v[18:19], v[48:49], v[32:33], v[170:171] op_sel:[0,1,0] op_sel_hi:[1,1,1] neg_lo:[0,1,0] neg_hi:[0,1,0]
	v_pk_fma_f32 v[20:21], v[48:49], v[34:35], v[172:173] op_sel_hi:[1,0,1] neg_lo:[0,1,0] neg_hi:[0,1,0]
	v_pk_fma_f32 v[22:23], v[48:49], v[34:35], v[174:175] op_sel:[0,1,0] op_sel_hi:[1,1,1] neg_lo:[0,1,0] neg_hi:[0,1,0]
	ds_read_b128 v[24:27], v2 offset:18432
	ds_read_b32 v44, v3 offset:14336
	ds_read_b32 v45, v53 offset:14336
	ds_read_b128 v[36:39], v2 offset:10240
	ds_read_b128 v[28:31], v2 offset:6144
	ds_read_b128 v[32:35], v2 offset:22528
	s_waitcnt lgkmcnt(7)
	v_pk_mul_f32 v[46:47], v[16:17], v[144:145] op_sel_hi:[1,0]
	v_pk_mul_f32 v[50:51], v[16:17], v[40:41] op_sel_hi:[1,0]
	v_pk_fma_f32 v[46:47], v[18:19], v[144:145], v[46:47] op_sel:[0,1,0] op_sel_hi:[1,1,1]
	v_pk_fma_f32 v[50:51], v[18:19], v[40:41], v[50:51] op_sel:[0,1,0] op_sel_hi:[1,1,1]
	v_pk_fma_f32 v[46:47], v[20:21], v[146:147], v[46:47] op_sel_hi:[1,0,1]
	v_pk_fma_f32 v[50:51], v[20:21], v[42:43], v[50:51] op_sel_hi:[1,0,1]
	v_pk_fma_f32 v[46:47], v[22:23], v[146:147], v[46:47] op_sel:[0,1,0] op_sel_hi:[1,1,1]
	v_pk_fma_f32 v[50:51], v[22:23], v[42:43], v[50:51] op_sel:[0,1,0] op_sel_hi:[1,1,1]
	ds_read_b128 v[40:43], v2 offset:2048
	v_pk_mul_f32 v[168:169], v[164:165], v[156:157] op_sel_hi:[1,0]
	v_add_f32_dpp v48, v47, v46 quad_perm:[1,0,3,2] row_mask:0xf bank_mask:0xf bound_ctrl:1
	v_add_f32_dpp v52, v51, v50 quad_perm:[1,0,3,2] row_mask:0xf bank_mask:0xf bound_ctrl:1
	v_pk_mul_f32 v[170:171], v[164:165], v[156:157] op_sel:[0,1] op_sel_hi:[1,1]
	v_add_f32_dpp v48, v48, v48 quad_perm:[2,3,0,1] row_mask:0xf bank_mask:0xf bound_ctrl:1
	ds_write_b32 v0, v52 offset:55296
	v_pk_mul_f32 v[172:173], v[164:165], v[158:159] op_sel_hi:[1,0]
	v_pk_mul_f32 v[174:175], v[164:165], v[158:159] op_sel:[0,1] op_sel_hi:[1,1]
	v_add_f32_dpp v48, v48, v48 row_ror:4 row_mask:0xf bank_mask:0xf bound_ctrl:1
	v_pk_fma_f32 v[168:169], v[16:17], v[148:149], v[168:169] op_sel_hi:[1,0,1]
	v_pk_fma_f32 v[170:171], v[18:19], v[148:149], v[170:171] op_sel:[0,1,0] op_sel_hi:[1,1,1]
	v_add_f32_dpp v48, v48, v48 row_ror:8 row_mask:0xf bank_mask:0xf bound_ctrl:1
	v_pk_fma_f32 v[172:173], v[20:21], v[150:151], v[172:173] op_sel_hi:[1,0,1]
	v_pk_fma_f32 v[174:175], v[22:23], v[150:151], v[174:175] op_sel:[0,1,0] op_sel_hi:[1,1,1]
	v_mov_b32_dpp v49, v48 quad_perm:[1,0,3,2] row_mask:0xf bank_mask:0xf bound_ctrl:1
	v_pk_fma_f32 v[16:17], v[48:49], v[152:153], v[168:169] op_sel_hi:[1,0,1] neg_lo:[0,1,0] neg_hi:[0,1,0]
	v_pk_fma_f32 v[18:19], v[48:49], v[152:153], v[170:171] op_sel:[0,1,0] op_sel_hi:[1,1,1] neg_lo:[0,1,0] neg_hi:[0,1,0]
	v_pk_fma_f32 v[20:21], v[48:49], v[154:155], v[172:173] op_sel_hi:[1,0,1] neg_lo:[0,1,0] neg_hi:[0,1,0]
	v_pk_fma_f32 v[22:23], v[48:49], v[154:155], v[174:175] op_sel:[0,1,0] op_sel_hi:[1,1,1] neg_lo:[0,1,0] neg_hi:[0,1,0]
	ds_read_b128 v[144:147], v2 offset:18688
	ds_read_b32 v164, v3 offset:14592
	ds_read_b32 v165, v53 offset:14592
	ds_read_b128 v[156:159], v2 offset:10496
	ds_read_b128 v[148:151], v2 offset:6400
	ds_read_b128 v[152:155], v2 offset:22784
	s_waitcnt lgkmcnt(7)
	v_pk_mul_f32 v[46:47], v[16:17], v[24:25] op_sel_hi:[1,0]
	v_pk_mul_f32 v[50:51], v[16:17], v[160:161] op_sel_hi:[1,0]
	v_pk_fma_f32 v[46:47], v[18:19], v[24:25], v[46:47] op_sel:[0,1,0] op_sel_hi:[1,1,1]
	v_pk_fma_f32 v[50:51], v[18:19], v[160:161], v[50:51] op_sel:[0,1,0] op_sel_hi:[1,1,1]
	v_pk_fma_f32 v[46:47], v[20:21], v[26:27], v[46:47] op_sel_hi:[1,0,1]
	v_pk_fma_f32 v[50:51], v[20:21], v[162:163], v[50:51] op_sel_hi:[1,0,1]
	v_pk_fma_f32 v[46:47], v[22:23], v[26:27], v[46:47] op_sel:[0,1,0] op_sel_hi:[1,1,1]
	v_pk_fma_f32 v[50:51], v[22:23], v[162:163], v[50:51] op_sel:[0,1,0] op_sel_hi:[1,1,1]
	ds_read_b128 v[160:163], v2 offset:2304
	v_pk_mul_f32 v[168:169], v[44:45], v[36:37] op_sel_hi:[1,0]
	v_add_f32_dpp v48, v47, v46 quad_perm:[1,0,3,2] row_mask:0xf bank_mask:0xf bound_ctrl:1
	v_add_f32_dpp v52, v51, v50 quad_perm:[1,0,3,2] row_mask:0xf bank_mask:0xf bound_ctrl:1
	v_pk_mul_f32 v[170:171], v[44:45], v[36:37] op_sel:[0,1] op_sel_hi:[1,1]
	v_add_f32_dpp v48, v48, v48 quad_perm:[2,3,0,1] row_mask:0xf bank_mask:0xf bound_ctrl:1
	ds_write_b32 v0, v52 offset:56320
	v_pk_mul_f32 v[172:173], v[44:45], v[38:39] op_sel_hi:[1,0]
	v_pk_mul_f32 v[174:175], v[44:45], v[38:39] op_sel:[0,1] op_sel_hi:[1,1]
	v_add_f32_dpp v48, v48, v48 row_ror:4 row_mask:0xf bank_mask:0xf bound_ctrl:1
	v_pk_fma_f32 v[168:169], v[16:17], v[28:29], v[168:169] op_sel_hi:[1,0,1]
	v_pk_fma_f32 v[170:171], v[18:19], v[28:29], v[170:171] op_sel:[0,1,0] op_sel_hi:[1,1,1]
	v_add_f32_dpp v48, v48, v48 row_ror:8 row_mask:0xf bank_mask:0xf bound_ctrl:1
	v_pk_fma_f32 v[172:173], v[20:21], v[30:31], v[172:173] op_sel_hi:[1,0,1]
	v_pk_fma_f32 v[174:175], v[22:23], v[30:31], v[174:175] op_sel:[0,1,0] op_sel_hi:[1,1,1]
	v_mov_b32_dpp v49, v48 quad_perm:[1,0,3,2] row_mask:0xf bank_mask:0xf bound_ctrl:1
	v_pk_fma_f32 v[16:17], v[48:49], v[32:33], v[168:169] op_sel_hi:[1,0,1] neg_lo:[0,1,0] neg_hi:[0,1,0]
	v_pk_fma_f32 v[18:19], v[48:49], v[32:33], v[170:171] op_sel:[0,1,0] op_sel_hi:[1,1,1] neg_lo:[0,1,0] neg_hi:[0,1,0]
	v_pk_fma_f32 v[20:21], v[48:49], v[34:35], v[172:173] op_sel_hi:[1,0,1] neg_lo:[0,1,0] neg_hi:[0,1,0]
	v_pk_fma_f32 v[22:23], v[48:49], v[34:35], v[174:175] op_sel:[0,1,0] op_sel_hi:[1,1,1] neg_lo:[0,1,0] neg_hi:[0,1,0]
	ds_read_b128 v[24:27], v2 offset:18944
	ds_read_b32 v44, v3 offset:14848
	ds_read_b32 v45, v53 offset:14848
	ds_read_b128 v[36:39], v2 offset:10752
	ds_read_b128 v[28:31], v2 offset:6656
	ds_read_b128 v[32:35], v2 offset:23040
	s_waitcnt lgkmcnt(7)
	v_pk_mul_f32 v[46:47], v[16:17], v[144:145] op_sel_hi:[1,0]
	v_pk_mul_f32 v[50:51], v[16:17], v[40:41] op_sel_hi:[1,0]
	v_pk_fma_f32 v[46:47], v[18:19], v[144:145], v[46:47] op_sel:[0,1,0] op_sel_hi:[1,1,1]
	v_pk_fma_f32 v[50:51], v[18:19], v[40:41], v[50:51] op_sel:[0,1,0] op_sel_hi:[1,1,1]
	v_pk_fma_f32 v[46:47], v[20:21], v[146:147], v[46:47] op_sel_hi:[1,0,1]
	v_pk_fma_f32 v[50:51], v[20:21], v[42:43], v[50:51] op_sel_hi:[1,0,1]
	v_pk_fma_f32 v[46:47], v[22:23], v[146:147], v[46:47] op_sel:[0,1,0] op_sel_hi:[1,1,1]
	v_pk_fma_f32 v[50:51], v[22:23], v[42:43], v[50:51] op_sel:[0,1,0] op_sel_hi:[1,1,1]
	ds_read_b128 v[40:43], v2 offset:2560
	v_pk_mul_f32 v[168:169], v[164:165], v[156:157] op_sel_hi:[1,0]
	v_add_f32_dpp v48, v47, v46 quad_perm:[1,0,3,2] row_mask:0xf bank_mask:0xf bound_ctrl:1
	v_add_f32_dpp v52, v51, v50 quad_perm:[1,0,3,2] row_mask:0xf bank_mask:0xf bound_ctrl:1
	v_pk_mul_f32 v[170:171], v[164:165], v[156:157] op_sel:[0,1] op_sel_hi:[1,1]
	v_add_f32_dpp v48, v48, v48 quad_perm:[2,3,0,1] row_mask:0xf bank_mask:0xf bound_ctrl:1
	ds_write_b32 v0, v52 offset:57344
	v_pk_mul_f32 v[172:173], v[164:165], v[158:159] op_sel_hi:[1,0]
	v_pk_mul_f32 v[174:175], v[164:165], v[158:159] op_sel:[0,1] op_sel_hi:[1,1]
	v_add_f32_dpp v48, v48, v48 row_ror:4 row_mask:0xf bank_mask:0xf bound_ctrl:1
	v_pk_fma_f32 v[168:169], v[16:17], v[148:149], v[168:169] op_sel_hi:[1,0,1]
	v_pk_fma_f32 v[170:171], v[18:19], v[148:149], v[170:171] op_sel:[0,1,0] op_sel_hi:[1,1,1]
	v_add_f32_dpp v48, v48, v48 row_ror:8 row_mask:0xf bank_mask:0xf bound_ctrl:1
	v_pk_fma_f32 v[172:173], v[20:21], v[150:151], v[172:173] op_sel_hi:[1,0,1]
	v_pk_fma_f32 v[174:175], v[22:23], v[150:151], v[174:175] op_sel:[0,1,0] op_sel_hi:[1,1,1]
	v_mov_b32_dpp v49, v48 quad_perm:[1,0,3,2] row_mask:0xf bank_mask:0xf bound_ctrl:1
	v_pk_fma_f32 v[16:17], v[48:49], v[152:153], v[168:169] op_sel_hi:[1,0,1] neg_lo:[0,1,0] neg_hi:[0,1,0]
	v_pk_fma_f32 v[18:19], v[48:49], v[152:153], v[170:171] op_sel:[0,1,0] op_sel_hi:[1,1,1] neg_lo:[0,1,0] neg_hi:[0,1,0]
	v_pk_fma_f32 v[20:21], v[48:49], v[154:155], v[172:173] op_sel_hi:[1,0,1] neg_lo:[0,1,0] neg_hi:[0,1,0]
	v_pk_fma_f32 v[22:23], v[48:49], v[154:155], v[174:175] op_sel:[0,1,0] op_sel_hi:[1,1,1] neg_lo:[0,1,0] neg_hi:[0,1,0]
	ds_read_b128 v[144:147], v2 offset:19200
	ds_read_b32 v164, v3 offset:15104
	ds_read_b32 v165, v53 offset:15104
	ds_read_b128 v[156:159], v2 offset:11008
	ds_read_b128 v[148:151], v2 offset:6912
	ds_read_b128 v[152:155], v2 offset:23296
	s_waitcnt lgkmcnt(7)
	v_pk_mul_f32 v[46:47], v[16:17], v[24:25] op_sel_hi:[1,0]
	v_pk_mul_f32 v[50:51], v[16:17], v[160:161] op_sel_hi:[1,0]
	v_pk_fma_f32 v[46:47], v[18:19], v[24:25], v[46:47] op_sel:[0,1,0] op_sel_hi:[1,1,1]
	v_pk_fma_f32 v[50:51], v[18:19], v[160:161], v[50:51] op_sel:[0,1,0] op_sel_hi:[1,1,1]
	v_pk_fma_f32 v[46:47], v[20:21], v[26:27], v[46:47] op_sel_hi:[1,0,1]
	v_pk_fma_f32 v[50:51], v[20:21], v[162:163], v[50:51] op_sel_hi:[1,0,1]
	v_pk_fma_f32 v[46:47], v[22:23], v[26:27], v[46:47] op_sel:[0,1,0] op_sel_hi:[1,1,1]
	v_pk_fma_f32 v[50:51], v[22:23], v[162:163], v[50:51] op_sel:[0,1,0] op_sel_hi:[1,1,1]
	ds_read_b128 v[160:163], v2 offset:2816
	v_pk_mul_f32 v[168:169], v[44:45], v[36:37] op_sel_hi:[1,0]
	v_add_f32_dpp v48, v47, v46 quad_perm:[1,0,3,2] row_mask:0xf bank_mask:0xf bound_ctrl:1
	v_add_f32_dpp v52, v51, v50 quad_perm:[1,0,3,2] row_mask:0xf bank_mask:0xf bound_ctrl:1
	v_pk_mul_f32 v[170:171], v[44:45], v[36:37] op_sel:[0,1] op_sel_hi:[1,1]
	v_add_f32_dpp v48, v48, v48 quad_perm:[2,3,0,1] row_mask:0xf bank_mask:0xf bound_ctrl:1
	ds_write_b32 v0, v52 offset:58368
	v_pk_mul_f32 v[172:173], v[44:45], v[38:39] op_sel_hi:[1,0]
	v_pk_mul_f32 v[174:175], v[44:45], v[38:39] op_sel:[0,1] op_sel_hi:[1,1]
	v_add_f32_dpp v48, v48, v48 row_ror:4 row_mask:0xf bank_mask:0xf bound_ctrl:1
	v_pk_fma_f32 v[168:169], v[16:17], v[28:29], v[168:169] op_sel_hi:[1,0,1]
	v_pk_fma_f32 v[170:171], v[18:19], v[28:29], v[170:171] op_sel:[0,1,0] op_sel_hi:[1,1,1]
	v_add_f32_dpp v48, v48, v48 row_ror:8 row_mask:0xf bank_mask:0xf bound_ctrl:1
	v_pk_fma_f32 v[172:173], v[20:21], v[30:31], v[172:173] op_sel_hi:[1,0,1]
	v_pk_fma_f32 v[174:175], v[22:23], v[30:31], v[174:175] op_sel:[0,1,0] op_sel_hi:[1,1,1]
	v_mov_b32_dpp v49, v48 quad_perm:[1,0,3,2] row_mask:0xf bank_mask:0xf bound_ctrl:1
	v_pk_fma_f32 v[16:17], v[48:49], v[32:33], v[168:169] op_sel_hi:[1,0,1] neg_lo:[0,1,0] neg_hi:[0,1,0]
	v_pk_fma_f32 v[18:19], v[48:49], v[32:33], v[170:171] op_sel:[0,1,0] op_sel_hi:[1,1,1] neg_lo:[0,1,0] neg_hi:[0,1,0]
	v_pk_fma_f32 v[20:21], v[48:49], v[34:35], v[172:173] op_sel_hi:[1,0,1] neg_lo:[0,1,0] neg_hi:[0,1,0]
	v_pk_fma_f32 v[22:23], v[48:49], v[34:35], v[174:175] op_sel:[0,1,0] op_sel_hi:[1,1,1] neg_lo:[0,1,0] neg_hi:[0,1,0]
	ds_read_b128 v[24:27], v2 offset:19456
	ds_read_b32 v44, v3 offset:15360
	ds_read_b32 v45, v53 offset:15360
	ds_read_b128 v[36:39], v2 offset:11264
	ds_read_b128 v[28:31], v2 offset:7168
	ds_read_b128 v[32:35], v2 offset:23552
	s_waitcnt lgkmcnt(7)
	v_pk_mul_f32 v[46:47], v[16:17], v[144:145] op_sel_hi:[1,0]
	v_pk_mul_f32 v[50:51], v[16:17], v[40:41] op_sel_hi:[1,0]
	v_pk_fma_f32 v[46:47], v[18:19], v[144:145], v[46:47] op_sel:[0,1,0] op_sel_hi:[1,1,1]
	v_pk_fma_f32 v[50:51], v[18:19], v[40:41], v[50:51] op_sel:[0,1,0] op_sel_hi:[1,1,1]
	v_pk_fma_f32 v[46:47], v[20:21], v[146:147], v[46:47] op_sel_hi:[1,0,1]
	v_pk_fma_f32 v[50:51], v[20:21], v[42:43], v[50:51] op_sel_hi:[1,0,1]
	v_pk_fma_f32 v[46:47], v[22:23], v[146:147], v[46:47] op_sel:[0,1,0] op_sel_hi:[1,1,1]
	v_pk_fma_f32 v[50:51], v[22:23], v[42:43], v[50:51] op_sel:[0,1,0] op_sel_hi:[1,1,1]
	ds_read_b128 v[40:43], v2 offset:3072
	v_pk_mul_f32 v[168:169], v[164:165], v[156:157] op_sel_hi:[1,0]
	v_add_f32_dpp v48, v47, v46 quad_perm:[1,0,3,2] row_mask:0xf bank_mask:0xf bound_ctrl:1
	v_add_f32_dpp v52, v51, v50 quad_perm:[1,0,3,2] row_mask:0xf bank_mask:0xf bound_ctrl:1
	v_pk_mul_f32 v[170:171], v[164:165], v[156:157] op_sel:[0,1] op_sel_hi:[1,1]
	v_add_f32_dpp v48, v48, v48 quad_perm:[2,3,0,1] row_mask:0xf bank_mask:0xf bound_ctrl:1
	ds_write_b32 v0, v52 offset:59392
	v_pk_mul_f32 v[172:173], v[164:165], v[158:159] op_sel_hi:[1,0]
	v_pk_mul_f32 v[174:175], v[164:165], v[158:159] op_sel:[0,1] op_sel_hi:[1,1]
	v_add_f32_dpp v48, v48, v48 row_ror:4 row_mask:0xf bank_mask:0xf bound_ctrl:1
	v_pk_fma_f32 v[168:169], v[16:17], v[148:149], v[168:169] op_sel_hi:[1,0,1]
	v_pk_fma_f32 v[170:171], v[18:19], v[148:149], v[170:171] op_sel:[0,1,0] op_sel_hi:[1,1,1]
	v_add_f32_dpp v48, v48, v48 row_ror:8 row_mask:0xf bank_mask:0xf bound_ctrl:1
	v_pk_fma_f32 v[172:173], v[20:21], v[150:151], v[172:173] op_sel_hi:[1,0,1]
	v_pk_fma_f32 v[174:175], v[22:23], v[150:151], v[174:175] op_sel:[0,1,0] op_sel_hi:[1,1,1]
	v_mov_b32_dpp v49, v48 quad_perm:[1,0,3,2] row_mask:0xf bank_mask:0xf bound_ctrl:1
	v_pk_fma_f32 v[16:17], v[48:49], v[152:153], v[168:169] op_sel_hi:[1,0,1] neg_lo:[0,1,0] neg_hi:[0,1,0]
	v_pk_fma_f32 v[18:19], v[48:49], v[152:153], v[170:171] op_sel:[0,1,0] op_sel_hi:[1,1,1] neg_lo:[0,1,0] neg_hi:[0,1,0]
	v_pk_fma_f32 v[20:21], v[48:49], v[154:155], v[172:173] op_sel_hi:[1,0,1] neg_lo:[0,1,0] neg_hi:[0,1,0]
	v_pk_fma_f32 v[22:23], v[48:49], v[154:155], v[174:175] op_sel:[0,1,0] op_sel_hi:[1,1,1] neg_lo:[0,1,0] neg_hi:[0,1,0]
	ds_read_b128 v[144:147], v2 offset:19712
	ds_read_b32 v164, v3 offset:15616
	ds_read_b32 v165, v53 offset:15616
	ds_read_b128 v[156:159], v2 offset:11520
	ds_read_b128 v[148:151], v2 offset:7424
	ds_read_b128 v[152:155], v2 offset:23808
	s_waitcnt lgkmcnt(7)
	v_pk_mul_f32 v[46:47], v[16:17], v[24:25] op_sel_hi:[1,0]
	v_pk_mul_f32 v[50:51], v[16:17], v[160:161] op_sel_hi:[1,0]
	v_pk_fma_f32 v[46:47], v[18:19], v[24:25], v[46:47] op_sel:[0,1,0] op_sel_hi:[1,1,1]
	v_pk_fma_f32 v[50:51], v[18:19], v[160:161], v[50:51] op_sel:[0,1,0] op_sel_hi:[1,1,1]
	v_pk_fma_f32 v[46:47], v[20:21], v[26:27], v[46:47] op_sel_hi:[1,0,1]
	v_pk_fma_f32 v[50:51], v[20:21], v[162:163], v[50:51] op_sel_hi:[1,0,1]
	v_pk_fma_f32 v[46:47], v[22:23], v[26:27], v[46:47] op_sel:[0,1,0] op_sel_hi:[1,1,1]
	v_pk_fma_f32 v[50:51], v[22:23], v[162:163], v[50:51] op_sel:[0,1,0] op_sel_hi:[1,1,1]
	ds_read_b128 v[160:163], v2 offset:3328
	v_pk_mul_f32 v[168:169], v[44:45], v[36:37] op_sel_hi:[1,0]
	v_add_f32_dpp v48, v47, v46 quad_perm:[1,0,3,2] row_mask:0xf bank_mask:0xf bound_ctrl:1
	v_add_f32_dpp v52, v51, v50 quad_perm:[1,0,3,2] row_mask:0xf bank_mask:0xf bound_ctrl:1
	v_pk_mul_f32 v[170:171], v[44:45], v[36:37] op_sel:[0,1] op_sel_hi:[1,1]
	v_add_f32_dpp v48, v48, v48 quad_perm:[2,3,0,1] row_mask:0xf bank_mask:0xf bound_ctrl:1
	ds_write_b32 v0, v52 offset:60416
	v_pk_mul_f32 v[172:173], v[44:45], v[38:39] op_sel_hi:[1,0]
	v_pk_mul_f32 v[174:175], v[44:45], v[38:39] op_sel:[0,1] op_sel_hi:[1,1]
	v_add_f32_dpp v48, v48, v48 row_ror:4 row_mask:0xf bank_mask:0xf bound_ctrl:1
	v_pk_fma_f32 v[168:169], v[16:17], v[28:29], v[168:169] op_sel_hi:[1,0,1]
	v_pk_fma_f32 v[170:171], v[18:19], v[28:29], v[170:171] op_sel:[0,1,0] op_sel_hi:[1,1,1]
	v_add_f32_dpp v48, v48, v48 row_ror:8 row_mask:0xf bank_mask:0xf bound_ctrl:1
	v_pk_fma_f32 v[172:173], v[20:21], v[30:31], v[172:173] op_sel_hi:[1,0,1]
	v_pk_fma_f32 v[174:175], v[22:23], v[30:31], v[174:175] op_sel:[0,1,0] op_sel_hi:[1,1,1]
	v_mov_b32_dpp v49, v48 quad_perm:[1,0,3,2] row_mask:0xf bank_mask:0xf bound_ctrl:1
	v_pk_fma_f32 v[16:17], v[48:49], v[32:33], v[168:169] op_sel_hi:[1,0,1] neg_lo:[0,1,0] neg_hi:[0,1,0]
	v_pk_fma_f32 v[18:19], v[48:49], v[32:33], v[170:171] op_sel:[0,1,0] op_sel_hi:[1,1,1] neg_lo:[0,1,0] neg_hi:[0,1,0]
	v_pk_fma_f32 v[20:21], v[48:49], v[34:35], v[172:173] op_sel_hi:[1,0,1] neg_lo:[0,1,0] neg_hi:[0,1,0]
	v_pk_fma_f32 v[22:23], v[48:49], v[34:35], v[174:175] op_sel:[0,1,0] op_sel_hi:[1,1,1] neg_lo:[0,1,0] neg_hi:[0,1,0]
	ds_read_b128 v[24:27], v2 offset:19968
	ds_read_b32 v44, v3 offset:15872
	ds_read_b32 v45, v53 offset:15872
	ds_read_b128 v[36:39], v2 offset:11776
	ds_read_b128 v[28:31], v2 offset:7680
	ds_read_b128 v[32:35], v2 offset:24064
	s_waitcnt lgkmcnt(7)
	v_pk_mul_f32 v[46:47], v[16:17], v[144:145] op_sel_hi:[1,0]
	v_pk_mul_f32 v[50:51], v[16:17], v[40:41] op_sel_hi:[1,0]
	v_pk_fma_f32 v[46:47], v[18:19], v[144:145], v[46:47] op_sel:[0,1,0] op_sel_hi:[1,1,1]
	v_pk_fma_f32 v[50:51], v[18:19], v[40:41], v[50:51] op_sel:[0,1,0] op_sel_hi:[1,1,1]
	v_pk_fma_f32 v[46:47], v[20:21], v[146:147], v[46:47] op_sel_hi:[1,0,1]
	v_pk_fma_f32 v[50:51], v[20:21], v[42:43], v[50:51] op_sel_hi:[1,0,1]
	v_pk_fma_f32 v[46:47], v[22:23], v[146:147], v[46:47] op_sel:[0,1,0] op_sel_hi:[1,1,1]
	v_pk_fma_f32 v[50:51], v[22:23], v[42:43], v[50:51] op_sel:[0,1,0] op_sel_hi:[1,1,1]
	ds_read_b128 v[40:43], v2 offset:3584
	v_pk_mul_f32 v[168:169], v[164:165], v[156:157] op_sel_hi:[1,0]
	v_add_f32_dpp v48, v47, v46 quad_perm:[1,0,3,2] row_mask:0xf bank_mask:0xf bound_ctrl:1
	v_add_f32_dpp v52, v51, v50 quad_perm:[1,0,3,2] row_mask:0xf bank_mask:0xf bound_ctrl:1
	v_pk_mul_f32 v[170:171], v[164:165], v[156:157] op_sel:[0,1] op_sel_hi:[1,1]
	v_add_f32_dpp v48, v48, v48 quad_perm:[2,3,0,1] row_mask:0xf bank_mask:0xf bound_ctrl:1
	ds_write_b32 v0, v52 offset:61440
	v_pk_mul_f32 v[172:173], v[164:165], v[158:159] op_sel_hi:[1,0]
	v_pk_mul_f32 v[174:175], v[164:165], v[158:159] op_sel:[0,1] op_sel_hi:[1,1]
	v_add_f32_dpp v48, v48, v48 row_ror:4 row_mask:0xf bank_mask:0xf bound_ctrl:1
	v_pk_fma_f32 v[168:169], v[16:17], v[148:149], v[168:169] op_sel_hi:[1,0,1]
	v_pk_fma_f32 v[170:171], v[18:19], v[148:149], v[170:171] op_sel:[0,1,0] op_sel_hi:[1,1,1]
	v_add_f32_dpp v48, v48, v48 row_ror:8 row_mask:0xf bank_mask:0xf bound_ctrl:1
	v_pk_fma_f32 v[172:173], v[20:21], v[150:151], v[172:173] op_sel_hi:[1,0,1]
	v_pk_fma_f32 v[174:175], v[22:23], v[150:151], v[174:175] op_sel:[0,1,0] op_sel_hi:[1,1,1]
	v_mov_b32_dpp v49, v48 quad_perm:[1,0,3,2] row_mask:0xf bank_mask:0xf bound_ctrl:1
	v_pk_fma_f32 v[16:17], v[48:49], v[152:153], v[168:169] op_sel_hi:[1,0,1] neg_lo:[0,1,0] neg_hi:[0,1,0]
	v_pk_fma_f32 v[18:19], v[48:49], v[152:153], v[170:171] op_sel:[0,1,0] op_sel_hi:[1,1,1] neg_lo:[0,1,0] neg_hi:[0,1,0]
	v_pk_fma_f32 v[20:21], v[48:49], v[154:155], v[172:173] op_sel_hi:[1,0,1] neg_lo:[0,1,0] neg_hi:[0,1,0]
	v_pk_fma_f32 v[22:23], v[48:49], v[154:155], v[174:175] op_sel:[0,1,0] op_sel_hi:[1,1,1] neg_lo:[0,1,0] neg_hi:[0,1,0]
	ds_read_b128 v[144:147], v2 offset:20224
	ds_read_b32 v164, v3 offset:16128
	ds_read_b32 v165, v53 offset:16128
	ds_read_b128 v[156:159], v2 offset:12032
	ds_read_b128 v[148:151], v2 offset:7936
	ds_read_b128 v[152:155], v2 offset:24320
	s_waitcnt lgkmcnt(7)
	v_pk_mul_f32 v[46:47], v[16:17], v[24:25] op_sel_hi:[1,0]
	v_pk_mul_f32 v[50:51], v[16:17], v[160:161] op_sel_hi:[1,0]
	v_pk_fma_f32 v[46:47], v[18:19], v[24:25], v[46:47] op_sel:[0,1,0] op_sel_hi:[1,1,1]
	v_pk_fma_f32 v[50:51], v[18:19], v[160:161], v[50:51] op_sel:[0,1,0] op_sel_hi:[1,1,1]
	v_pk_fma_f32 v[46:47], v[20:21], v[26:27], v[46:47] op_sel_hi:[1,0,1]
	v_pk_fma_f32 v[50:51], v[20:21], v[162:163], v[50:51] op_sel_hi:[1,0,1]
	v_pk_fma_f32 v[46:47], v[22:23], v[26:27], v[46:47] op_sel:[0,1,0] op_sel_hi:[1,1,1]
	v_pk_fma_f32 v[50:51], v[22:23], v[162:163], v[50:51] op_sel:[0,1,0] op_sel_hi:[1,1,1]
	ds_read_b128 v[160:163], v2 offset:3840
	v_pk_mul_f32 v[168:169], v[44:45], v[36:37] op_sel_hi:[1,0]
	v_add_f32_dpp v48, v47, v46 quad_perm:[1,0,3,2] row_mask:0xf bank_mask:0xf bound_ctrl:1
	v_add_f32_dpp v52, v51, v50 quad_perm:[1,0,3,2] row_mask:0xf bank_mask:0xf bound_ctrl:1
	v_pk_mul_f32 v[170:171], v[44:45], v[36:37] op_sel:[0,1] op_sel_hi:[1,1]
	v_add_f32_dpp v48, v48, v48 quad_perm:[2,3,0,1] row_mask:0xf bank_mask:0xf bound_ctrl:1
	ds_write_b32 v0, v52 offset:62464
	v_pk_mul_f32 v[172:173], v[44:45], v[38:39] op_sel_hi:[1,0]
	v_pk_mul_f32 v[174:175], v[44:45], v[38:39] op_sel:[0,1] op_sel_hi:[1,1]
	v_add_f32_dpp v48, v48, v48 row_ror:4 row_mask:0xf bank_mask:0xf bound_ctrl:1
	v_pk_fma_f32 v[168:169], v[16:17], v[28:29], v[168:169] op_sel_hi:[1,0,1]
	v_pk_fma_f32 v[170:171], v[18:19], v[28:29], v[170:171] op_sel:[0,1,0] op_sel_hi:[1,1,1]
	v_add_f32_dpp v48, v48, v48 row_ror:8 row_mask:0xf bank_mask:0xf bound_ctrl:1
	v_pk_fma_f32 v[172:173], v[20:21], v[30:31], v[172:173] op_sel_hi:[1,0,1]
	v_pk_fma_f32 v[174:175], v[22:23], v[30:31], v[174:175] op_sel:[0,1,0] op_sel_hi:[1,1,1]
	v_mov_b32_dpp v49, v48 quad_perm:[1,0,3,2] row_mask:0xf bank_mask:0xf bound_ctrl:1
	v_pk_fma_f32 v[16:17], v[48:49], v[32:33], v[168:169] op_sel_hi:[1,0,1] neg_lo:[0,1,0] neg_hi:[0,1,0]
	v_pk_fma_f32 v[18:19], v[48:49], v[32:33], v[170:171] op_sel:[0,1,0] op_sel_hi:[1,1,1] neg_lo:[0,1,0] neg_hi:[0,1,0]
	v_pk_fma_f32 v[20:21], v[48:49], v[34:35], v[172:173] op_sel_hi:[1,0,1] neg_lo:[0,1,0] neg_hi:[0,1,0]
	v_pk_fma_f32 v[22:23], v[48:49], v[34:35], v[174:175] op_sel:[0,1,0] op_sel_hi:[1,1,1] neg_lo:[0,1,0] neg_hi:[0,1,0]
	s_waitcnt lgkmcnt(1)
	v_pk_mul_f32 v[46:47], v[16:17], v[144:145] op_sel_hi:[1,0]
	v_pk_mul_f32 v[50:51], v[16:17], v[40:41] op_sel_hi:[1,0]
	v_pk_fma_f32 v[46:47], v[18:19], v[144:145], v[46:47] op_sel:[0,1,0] op_sel_hi:[1,1,1]
	v_pk_fma_f32 v[50:51], v[18:19], v[40:41], v[50:51] op_sel:[0,1,0] op_sel_hi:[1,1,1]
	v_pk_fma_f32 v[46:47], v[20:21], v[146:147], v[46:47] op_sel_hi:[1,0,1]
	v_pk_fma_f32 v[50:51], v[20:21], v[42:43], v[50:51] op_sel_hi:[1,0,1]
	v_pk_fma_f32 v[46:47], v[22:23], v[146:147], v[46:47] op_sel:[0,1,0] op_sel_hi:[1,1,1]
	v_pk_fma_f32 v[50:51], v[22:23], v[42:43], v[50:51] op_sel:[0,1,0] op_sel_hi:[1,1,1]
	v_pk_mul_f32 v[168:169], v[164:165], v[156:157] op_sel_hi:[1,0]
	v_add_f32_dpp v48, v47, v46 quad_perm:[1,0,3,2] row_mask:0xf bank_mask:0xf bound_ctrl:1
	v_add_f32_dpp v52, v51, v50 quad_perm:[1,0,3,2] row_mask:0xf bank_mask:0xf bound_ctrl:1
	v_pk_mul_f32 v[170:171], v[164:165], v[156:157] op_sel:[0,1] op_sel_hi:[1,1]
	v_add_f32_dpp v48, v48, v48 quad_perm:[2,3,0,1] row_mask:0xf bank_mask:0xf bound_ctrl:1
	ds_write_b32 v0, v52 offset:63488
	v_pk_mul_f32 v[172:173], v[164:165], v[158:159] op_sel_hi:[1,0]
	v_pk_mul_f32 v[174:175], v[164:165], v[158:159] op_sel:[0,1] op_sel_hi:[1,1]
	v_add_f32_dpp v48, v48, v48 row_ror:4 row_mask:0xf bank_mask:0xf bound_ctrl:1
	v_pk_fma_f32 v[168:169], v[16:17], v[148:149], v[168:169] op_sel_hi:[1,0,1]
	v_pk_fma_f32 v[170:171], v[18:19], v[148:149], v[170:171] op_sel:[0,1,0] op_sel_hi:[1,1,1]
	v_add_f32_dpp v48, v48, v48 row_ror:8 row_mask:0xf bank_mask:0xf bound_ctrl:1
	v_pk_fma_f32 v[172:173], v[20:21], v[150:151], v[172:173] op_sel_hi:[1,0,1]
	v_pk_fma_f32 v[174:175], v[22:23], v[150:151], v[174:175] op_sel:[0,1,0] op_sel_hi:[1,1,1]
	v_mov_b32_dpp v49, v48 quad_perm:[1,0,3,2] row_mask:0xf bank_mask:0xf bound_ctrl:1
	v_pk_fma_f32 v[16:17], v[48:49], v[152:153], v[168:169] op_sel_hi:[1,0,1] neg_lo:[0,1,0] neg_hi:[0,1,0]
	v_pk_fma_f32 v[18:19], v[48:49], v[152:153], v[170:171] op_sel:[0,1,0] op_sel_hi:[1,1,1] neg_lo:[0,1,0] neg_hi:[0,1,0]
	v_pk_fma_f32 v[20:21], v[48:49], v[154:155], v[172:173] op_sel_hi:[1,0,1] neg_lo:[0,1,0] neg_hi:[0,1,0]
	v_pk_fma_f32 v[22:23], v[48:49], v[154:155], v[174:175] op_sel:[0,1,0] op_sel_hi:[1,1,1] neg_lo:[0,1,0] neg_hi:[0,1,0]
	v_pk_mul_f32 v[50:51], v[16:17], v[160:161] op_sel_hi:[1,0]
	v_pk_fma_f32 v[50:51], v[18:19], v[160:161], v[50:51] op_sel:[0,1,0] op_sel_hi:[1,1,1]
	v_pk_fma_f32 v[50:51], v[20:21], v[162:163], v[50:51] op_sel_hi:[1,0,1]
	v_pk_fma_f32 v[50:51], v[22:23], v[162:163], v[50:51] op_sel:[0,1,0] op_sel_hi:[1,1,1]
	s_nop 1
	v_add_f32_dpp v52, v51, v50 quad_perm:[1,0,3,2] row_mask:0xf bank_mask:0xf bound_ctrl:1
	ds_write_b32 v0, v52 offset:64512
	s_setprio 0
